# v13 plus HGRN output loop: the four per-token partial-sum DPP reductions interleaved (hazard pads and three exec-mask toggles removed, same ops per value)
# baseline (speedup 1.0000x reference)
; #define HGO_LOAD(QV, KV, CJ) { const int cj_ = (CJ) < 64 ? (CJ) : 63; const size_t tb_ = ((((m0 >> 4) + cj_) * 8 + h) * 8) * 256 + fr * 16 + 4 * fq; \
;           _Pragma("unroll") for (int x = 0; x < 8; ++x) { QV[x] = *(const v2u*)(QT + tb_ + 256 * x); KV[x] = *(const v2u*)(KTL + tb_ + 256 * x); } }
; __device__ __forceinline__ void hg_out(const bf16* QT, const bf16* KTL, const bf16* KT, const bf16* IV, const float* DB, const float* SL, const float* DT, const float* norm_g, bf16* SGO, LAS unsigned char* lds) {
;     ...
;         HGO_LOAD(q1, k1, 0) HGO_LOAD(q2, k2, 1) HGO_LOADV(0)
;         for (int ci = 0; ci < 64; ++ci) {
;             const size_t chunk = (m0 >> 4) + ci, mrow = m0 + 16 * ci;
;             v2u ktv[8]; f32x4 dv[8];
; #pragma unroll
;             for (int kt = 0; kt < 8; ++kt) { ktv[kt] = *(const v2u*)(KT + (chunk * 1024 + 128 * h + 16 * kt + fr) * 16 + 4 * fq); dv[kt] = *(const f32x4*)(DB + chunk * 1024 + 128 * h + 16 * kt + 4 * fq); }
;             const unsigned v0 = vn[0], v1 = vn[1], v2 = vn[2], v3 = vn[3];
;             bf16* gp = SGO + (mrow + 4 * fq) * 1024 + 128 * h + 16 * w + fr;
;             const float sg0 = bf1(gn[0]), sg1 = bf1(gn[1]), sg2 = bf1(gn[2]), sg3 = bf1(gn[3]);
;             HGO_LOADV(ci + 1)
;             v2u qc[8], kc[8];
; #pragma unroll
;             for (int x = 0; x < 8; ++x) { qc[x] = q1[x]; kc[x] = k1[x]; q1[x] = q2[x]; k1[x] = k2[x]; }
;             HGO_LOAD(q2, k2, ci + 2)
;             const bf16x8 vb = mk8(v0 | (v1 << 16), v2 | (v3 << 16), 0u, 0u);
;             f32x4 pt = (f32x4){0.f, 0.f, 0.f, 0.f};
; #pragma unroll
;             for (int p = 0; p < 4; ++p) pt = __builtin_amdgcn_mfma_f32_16x16x32_bf16(mk8(kc[2 * p].x, kc[2 * p].y, kc[2 * p + 1].x, kc[2 * p + 1].y), mk8(qc[2 * p].x, qc[2 * p].y, qc[2 * p + 1].x, qc[2 * p + 1].y), pt, 0, 0, 0);
; #pragma unroll
;             for (int i = 0; i < 4; ++i) if (4 * fq + i > fr) pt[i] = 0.f;
.LBB0_2135:
	global_load_dwordx2 v[106:107], v[198:199], off offset:-2048
	s_add_u32 s52, s48, 16
	s_addc_u32 s53, s49, 0
	global_load_dwordx4 v[64:67], v[190:191], off offset:-256
	global_load_dwordx4 v[60:63], v[190:191], off offset:-192
	global_load_dwordx2 v[110:111], v[198:199], off offset:-1536
	global_load_dwordx2 v[32:33], v[198:199], off offset:-1024
	global_load_dwordx2 v[164:165], v[198:199], off offset:-512
	global_load_dwordx4 v[56:59], v[190:191], off offset:-128
	global_load_dwordx4 v[52:55], v[190:191], off offset:-64
	global_load_dwordx4 v[48:51], v[190:191], off
	global_load_dwordx4 v[44:47], v[190:191], off offset:64
	global_load_dwordx2 v[168:169], v[198:199], off
	global_load_dwordx2 v[172:173], v[198:199], off offset:512
	global_load_dwordx2 v[88:89], v[198:199], off offset:1024
	global_load_dwordx2 v[84:85], v[198:199], off offset:1536
	global_load_dwordx4 v[40:43], v[190:191], off offset:128
	global_load_dwordx4 v[36:39], v[190:191], off offset:192
	s_cmpk_eq_i32 s48, 0x3f0
	s_cselect_b32 s92, s48, s52
	v_lshl_add_u64 v[34:35], v[182:183], 0, s[92:93]
	v_lshlrev_b64 v[34:35], 11, v[34:35]
	s_min_u32 s54, s59, 61
	v_lshl_add_u64 v[86:87], v[186:187], 0, v[34:35]
	s_add_i32 s54, s54, 2
	v_add_co_u32_e32 v108, vcc, s25, v86
	s_add_u32 s54, s18, s54
	v_lshl_add_u64 v[34:35], v[184:185], 0, v[34:35]
	v_addc_co_u32_e32 v109, vcc, 0, v87, vcc
	s_addc_u32 s55, s19, 0
	v_add_co_u32_e32 v112, vcc, s25, v34
	s_lshl_b64 s[54:55], s[54:55], 15
	s_waitcnt vmcnt(23)
	v_mov_b32_e32 v114, v239
	s_waitcnt vmcnt(22)
	v_mov_b32_e32 v115, v240
	s_waitcnt vmcnt(21)
	v_mov_b32_e32 v166, v241
	s_waitcnt vmcnt(20)
	v_mov_b32_e32 v167, v242
	v_addc_co_u32_e32 v113, vcc, 0, v35, vcc
	global_load_ushort v239, v[86:87], off
	global_load_ushort v240, v[86:87], off offset:2048
	global_load_ushort v241, v[108:109], off
	global_load_ushort v242, v[108:109], off offset:2048
	global_load_ushort v243, v[34:35], off
	global_load_ushort v244, v[112:113], off
	global_load_ushort v246, v[112:113], off offset:2048
	global_load_ushort v245, v[34:35], off offset:2048
	v_lshl_or_b32 v34, v188, 1, s54
	v_mov_b32_e32 v35, s55
	v_lshl_add_u64 v[86:87], s[6:7], 0, v[34:35]
	v_mov_b64_e32 v[78:79], v[140:141]
	v_mov_b64_e32 v[76:77], v[138:139]
	v_mov_b64_e32 v[82:83], v[136:137]
	v_mov_b64_e32 v[80:81], v[134:135]
	v_mov_b64_e32 v[100:101], v[146:147]
	v_mov_b64_e32 v[98:99], v[144:145]
	v_mov_b64_e32 v[104:105], v[142:143]
	v_mov_b64_e32 v[102:103], v[150:151]
	v_mov_b64_e32 v[140:141], v[208:209]
	v_mov_b64_e32 v[138:139], v[202:203]
	v_mov_b64_e32 v[136:137], v[196:197]
	v_mov_b64_e32 v[134:135], v[194:195]
	v_mov_b64_e32 v[146:147], v[206:207]
	v_mov_b64_e32 v[144:145], v[204:205]
	v_mov_b64_e32 v[142:143], v[200:201]
	v_mov_b64_e32 v[150:151], v[192:193]
	v_lshl_add_u64 v[34:35], s[12:13], 0, v[34:35]
	global_load_dwordx2 v[194:195], v[86:87], off
	global_load_dwordx2 v[196:197], v[86:87], off offset:512
	global_load_dwordx2 v[202:203], v[86:87], off offset:1024
	global_load_dwordx2 v[208:209], v[86:87], off offset:1536
	global_load_dwordx2 v[192:193], v[34:35], off
	global_load_dwordx2 v[200:201], v[34:35], off offset:512
	global_load_dwordx2 v[204:205], v[34:35], off offset:1024
	global_load_dwordx2 v[206:207], v[34:35], off offset:1536
	v_mov_b64_e32 v[70:71], v[156:157]
	v_mov_b64_e32 v[68:69], v[154:155]
	v_mov_b64_e32 v[74:75], v[152:153]
	v_mov_b64_e32 v[72:73], v[148:149]
	v_mov_b64_e32 v[92:93], v[180:181]
	v_mov_b64_e32 v[90:91], v[162:163]
	v_mov_b64_e32 v[96:97], v[160:161]
	v_mov_b64_e32 v[94:95], v[158:159]
	v_mov_b64_e32 v[156:157], v[218:219]
	v_mov_b64_e32 v[154:155], v[214:215]
	v_mov_b64_e32 v[152:153], v[212:213]
	v_mov_b64_e32 v[148:149], v[210:211]
	v_mov_b64_e32 v[180:181], v[224:225]
	v_mov_b64_e32 v[162:163], v[222:223]
	v_mov_b64_e32 v[160:161], v[220:221]
	v_mov_b64_e32 v[158:159], v[216:217]
	global_load_dwordx2 v[210:211], v[86:87], off offset:2048
	global_load_dwordx2 v[212:213], v[86:87], off offset:2560
	global_load_dwordx2 v[214:215], v[86:87], off offset:3072
	global_load_dwordx2 v[218:219], v[86:87], off offset:3584
	global_load_dwordx2 v[216:217], v[34:35], off offset:2048
	global_load_dwordx2 v[220:221], v[34:35], off offset:2560
	global_load_dwordx2 v[222:223], v[34:35], off offset:3072
	global_load_dwordx2 v[224:225], v[34:35], off offset:3584
	v_mfma_f32_16x16x32_bf16 v[102:105], v[102:105], v[80:83], 0
	v_lshlrev_b32_e32 v34, 16, v115
	v_or_b32_sdwa v234, v34, v114 dst_sel:DWORD dst_unused:UNUSED_PAD src0_sel:DWORD src1_sel:WORD_0
	v_lshlrev_b32_e32 v34, 16, v167
	v_mfma_f32_16x16x32_bf16 v[98:101], v[98:101], v[76:79], v[102:105]
	v_or_b32_sdwa v235, v34, v166 dst_sel:DWORD dst_unused:UNUSED_PAD src0_sel:DWORD src1_sel:WORD_0
	v_mov_b32_e32 v34, s93
	v_mov_b32_e32 v108, v236
	v_mfma_f32_16x16x32_bf16 v[94:97], v[94:97], v[72:75], v[98:101]
	v_mov_b32_e32 v109, v236
	v_mov_b32_e32 v112, v236
	v_mov_b32_e32 v113, v236
	v_mfma_f32_16x16x32_bf16 v[176:179], v[90:93], v[68:71], v[94:97]
	v_mov_b32_e32 v35, v236
	v_mov_b32_e32 v166, v236
	v_mov_b32_e32 v167, v236
	v_mov_b32_e32 v237, v236
	v_mov_b32_e32 v170, v236
	s_nop 2
	v_cndmask_b32_e64 v34, v176, v34, s[40:41]
	v_cndmask_b32_e64 v176, v34, v176, s[42:43]
	v_mov_b32_e32 v34, v236
	s_waitcnt vmcnt(39)
; #define LAS __attribute__((address_space(3)))
; __device__ __forceinline__ unsigned pk2(float lo, float hi) { const f32x2_t v = {lo, hi}; const bf16x2_t b = __builtin_convertvector(v, bf16x2_t); return __builtin_bit_cast(unsigned, b); }
; __device__ __forceinline__ float row16_sum(float x) { x += dpp_f<0xB1>(x); x += dpp_f<0x4E>(x); x += dpp_f<0x141>(x); x += dpp_f<0x140>(x); return x; }
; __device__ __forceinline__ void hg_out(const bf16* QT, const bf16* KTL, const bf16* KT, const bf16* IV, const float* DB, const float* SL, const float* DT, const float* norm_g, bf16* SGO, LAS unsigned char* lds) {
;     ...
;             f32x4 o = (f32x4){0.f, 0.f, 0.f, 0.f};
; #pragma unroll
;             for (int p = 0; p < 4; ++p) {
;                 const bf16x8 sb = mk8(pk2(S[2 * p][0], S[2 * p][1]), pk2(S[2 * p][2], S[2 * p][3]), pk2(S[2 * p + 1][0], S[2 * p + 1][1]), pk2(S[2 * p + 1][2], S[2 * p + 1][3]));
;                 o = __builtin_amdgcn_mfma_f32_16x16x32_bf16(mk8(qc[2 * p].x, qc[2 * p].y, qc[2 * p + 1].x, qc[2 * p + 1].y), sb, o, 0, 0, 0);
;             }
;             o = __builtin_amdgcn_mfma_f32_16x16x32_bf16(mk8(pk2(pt[0], pt[1]), pk2(pt[2], pt[3]), 0u, 0u), vb, o, 0, 0, 0);
; #pragma unroll
;             for (int kt = 0; kt < 8; ++kt) { S[kt] = __builtin_amdgcn_mfma_f32_16x16x32_bf16(mk8(ktv[kt].x, ktv[kt].y, 0u, 0u), vb, S[kt], 0, 0, 0); S[kt] = S[kt] * dv[kt]; }
;             LAS float* sb_ = ssb + (ci & 1) * 128;
; #pragma unroll
;             for (int i = 0; i < 4; ++i) { const float ss = row16_sum(o[i] * o[i]); if (fr == 0) sb_[(4 * fq + i) * 8 + w] = ss; }
	v_mfma_f32_16x16x32_bf16 v[96:99], v[106:109], v[234:237], v[20:23]
	v_mov_b32_e32 v171, v236
	v_cndmask_b32_e64 v177, 0, v177, s[42:43]
	v_cndmask_b32_e64 v178, v178, 0, s[44:45]
	v_cvt_pk_bf16_f32 v20, v20, v21
	v_cvt_pk_bf16_f32 v21, v22, v23
	v_cvt_pk_bf16_f32 v22, v12, v13
	v_cvt_pk_bf16_f32 v23, v14, v15
	s_waitcnt vmcnt(36)
	v_mfma_f32_16x16x32_bf16 v[104:107], v[110:113], v[234:237], v[12:15]
	v_mov_b32_e32 v174, v236
	v_mov_b32_e32 v175, v236
	v_mov_b32_e32 v90, v236
	s_waitcnt vmcnt(35)
	v_mfma_f32_16x16x32_bf16 v[108:111], v[32:35], v[234:237], v[0:3]
	v_cvt_pk_bf16_f32 v12, v28, v29
	v_cvt_pk_bf16_f32 v13, v30, v31
	v_cvt_pk_bf16_f32 v14, v24, v25
	s_waitcnt vmcnt(34)
	v_mfma_f32_16x16x32_bf16 v[112:115], v[164:167], v[234:237], v[8:11]
	v_cvt_pk_bf16_f32 v0, v0, v1
	v_cvt_pk_bf16_f32 v1, v2, v3
	v_cvt_pk_bf16_f32 v2, v8, v9
	v_cvt_pk_bf16_f32 v3, v10, v11
	v_mfma_f32_16x16x32_bf16 v[8:11], v[80:83], v[20:23], 0
	v_cvt_pk_bf16_f32 v15, v26, v27
	v_mov_b32_e32 v91, v236
	v_mov_b32_e32 v86, v236
	v_mfma_f32_16x16x32_bf16 v[0:3], v[76:79], v[0:3], v[8:11]
	v_mov_b32_e32 v87, v236
	s_and_b32 s54, s58, 0x80
	s_lshl_b32 s54, s54, 2
	s_waitcnt vmcnt(29)
	v_mfma_f32_16x16x32_bf16 v[92:95], v[168:171], v[234:237], v[4:7]
	v_cndmask_b32_e64 v8, v179, 0, s[46:47]
	s_add_i32 s60, s54, 0
	s_lshl_b32 s54, s1, 2
	v_cvt_pk_bf16_f32 v4, v4, v5
	v_cvt_pk_bf16_f32 v5, v6, v7
	v_cvt_pk_bf16_f32 v6, v16, v17
	v_cvt_pk_bf16_f32 v7, v18, v19
	s_waitcnt vmcnt(28)
	v_mfma_f32_16x16x32_bf16 v[100:103], v[172:175], v[234:237], v[16:19]
	s_add_i32 s54, s60, s54
	v_mfma_f32_16x16x32_bf16 v[0:3], v[72:75], v[4:7], v[0:3]
	v_cvt_pk_bf16_f32 v4, v176, v177
	v_cvt_pk_bf16_f32 v5, v178, v8
	v_mov_b32_e32 v6, v236
	v_mov_b32_e32 v7, v236
	v_mfma_f32_16x16x32_bf16 v[0:3], v[68:71], v[12:15], v[0:3]
	s_nop 0
	v_mfma_f32_16x16x32_bf16 v[68:71], v[4:7], v[234:237], v[0:3]
	s_waitcnt vmcnt(27)
	v_mfma_f32_16x16x32_bf16 v[88:91], v[88:91], v[234:237], v[28:31]
	s_waitcnt vmcnt(26)
	v_mfma_f32_16x16x32_bf16 v[84:87], v[84:87], v[234:237], v[24:27]
	s_nop 3
	v_mul_f32_e32 v0, v68, v68
	v_mul_f32_e32 v1, v69, v69
	v_mul_f32_e32 v2, v70, v70
	v_mul_f32_e32 v3, v71, v71
	v_add_u32_e32 v34, s54, v125
	v_mov_b32_dpp v4, v0 quad_perm:[1,0,3,2] row_mask:0xf bank_mask:0xf bound_ctrl:1
	v_mov_b32_dpp v5, v1 quad_perm:[1,0,3,2] row_mask:0xf bank_mask:0xf bound_ctrl:1
	v_mov_b32_dpp v6, v2 quad_perm:[1,0,3,2] row_mask:0xf bank_mask:0xf bound_ctrl:1
	v_mov_b32_dpp v7, v3 quad_perm:[1,0,3,2] row_mask:0xf bank_mask:0xf bound_ctrl:1
	v_fmac_f32_e32 v4, v68, v68
	v_fmac_f32_e32 v5, v69, v69
	v_fmac_f32_e32 v6, v70, v70
	v_fmac_f32_e32 v7, v71, v71
	v_add_f32_dpp v4, v4, v4 quad_perm:[2,3,0,1] row_mask:0xf bank_mask:0xf bound_ctrl:1
	v_add_f32_dpp v5, v5, v5 quad_perm:[2,3,0,1] row_mask:0xf bank_mask:0xf bound_ctrl:1
	v_add_f32_dpp v6, v6, v6 quad_perm:[2,3,0,1] row_mask:0xf bank_mask:0xf bound_ctrl:1
	v_add_f32_dpp v7, v7, v7 quad_perm:[2,3,0,1] row_mask:0xf bank_mask:0xf bound_ctrl:1
	v_add_f32_dpp v0, v4, v4 row_half_mirror row_mask:0xf bank_mask:0xf bound_ctrl:1
	v_add_f32_dpp v1, v5, v5 row_half_mirror row_mask:0xf bank_mask:0xf bound_ctrl:1
	v_add_f32_dpp v2, v6, v6 row_half_mirror row_mask:0xf bank_mask:0xf bound_ctrl:1
	v_add_f32_dpp v3, v7, v7 row_half_mirror row_mask:0xf bank_mask:0xf bound_ctrl:1
	v_mov_b32_dpp v4, v0 row_mirror row_mask:0xf bank_mask:0xf bound_ctrl:1
	v_mov_b32_dpp v5, v1 row_mirror row_mask:0xf bank_mask:0xf bound_ctrl:1
	v_mov_b32_dpp v6, v2 row_mirror row_mask:0xf bank_mask:0xf bound_ctrl:1
	v_mov_b32_dpp v7, v3 row_mirror row_mask:0xf bank_mask:0xf bound_ctrl:1
	s_and_saveexec_b64 s[54:55], s[38:39]
	v_add_f32_e32 v0, v0, v4
	v_add_f32_e32 v1, v1, v5
	v_add_f32_e32 v2, v2, v6
	v_add_f32_e32 v3, v3, v7
	ds_write_b32 v34, v0
	ds_write_b32 v34, v1 offset:32
	ds_write_b32 v34, v2 offset:64
	ds_write_b32 v34, v3 offset:96
	s_branch .LBB0_2134
